# both GEMM K-loop heads aligned to 64 B (.p2align 6); previously at 60 / 36 mod 64
# speedup vs baseline: 1.0126x; 1.0043x over previous
; #define PG8_STAGE(bufoff, gbase, voff) do { _Pragma("unroll") for (int _i = 0; _i < 2; ++_i) \
;         __builtin_amdgcn_global_load_lds((const unsigned*)((const char*)(gbase) + (voff)[_i]), (LAS unsigned*)(lds + (bufoff) + ldsw + _i * 8192), 16, 0, 0); } while (0)
; #define PG8_LDA(dst, b, h) do { _Pragma("unroll") for (int m = 0; m < 4; ++m) _Pragma("unroll") for (int k = 0; k < 2; ++k) dst[m][k] = *(const LAS bf16x8*)(lds + PG8_SA(b, h) + aoff + m * 2048 + k * 1024); } while (0)
; #define PG8_LDB(dst, b, h) do { _Pragma("unroll") for (int n = 0; n < 2; ++n) _Pragma("unroll") for (int k = 0; k < 2; ++k) dst[n][k] = *(const LAS bf16x8*)(lds + PG8_SB(b, h) + boff + n * 2048 + k * 1024); } while (0)
; #define PG8_SCHED __builtin_amdgcn_sched_barrier(0)
; template <class Epi>
; DI void gemm_phase(LAS unsigned char* lds, const Gemm g, const StaticOrder& S, const Epi& E, const int tid) {
;     ...
;         const bool has_next = S.next(ui + 1, nxt);
;         const char* nA = has_next ? (const char*)g.A + (size_t)nxt.pm * tstepA : cA; const char* nB = has_next ? (const char*)g.Bt + (size_t)nxt.pn * tstepB : cB;
;         for (int t = 0; t < nt; t += 2) {
;             const bool last = (t == nt - 2);
;             const char* a1 = cA + PG8_KTA(t + 1);
;             const char* a2 = last ? nA : cA + PG8_KTA(t + 2); const char* b2 = last ? nB : cB + (size_t)(t + 2) * kstep;
;             const char* a3 = last ? nA + PG8_KTA(1) : cA + PG8_KTA(t + 3); const char* b3 = b2 + kstep;
;             PG8_LDB(B0, 0, 0); PG8_SCHED; PG8_LDA(At, 0, 0); PG8_STAGE(PG8_SA(1, 1), a1 + hstepA, voffA);
;     ...
;         for (int a = 0; a < 2; ++a)
; #pragma unroll
;             for (int b = 0; b < 2; ++b)
; #pragma unroll
;                 for (int m = 0; m < 4; ++m)
; #pragma unroll
;                     for (int n = 0; n < 2; ++n) acc[a][b][m][n] = (f32x4){0.f, 0.f, 0.f, 0.f};
.LBB0_61:
	s_ashr_i32 s43, s42, 31
	v_cmp_lt_i64_e32 vcc, s[6:7], v[142:143]
	s_lshl_b64 s[6:7], s[42:43], 20
	s_add_u32 s46, s70, s6
	s_addc_u32 s47, s71, s7
	s_and_b64 s[6:7], vcc, exec
	s_cselect_b32 s30, s47, s45
	s_cselect_b32 s31, s46, s44
	s_ashr_i32 s39, s38, 31
	s_lshl_b64 s[6:7], s[38:39], 20
	s_add_u32 s48, s36, s6
	s_addc_u32 s49, s37, s7
	s_and_b64 s[6:7], vcc, exec
	s_cselect_b32 s39, s49, s5
	s_cselect_b32 s43, s48, s4
	s_add_u32 s64, s31, 0x80
	s_addc_u32 s65, s30, 0
	s_add_u32 s6, s44, 0x80080
	s_addc_u32 s7, s45, 0
	s_add_u32 s66, s4, 0x100
	v_mov_b64_e32 v[2:3], 0
	s_addc_u32 s67, s5, 0
	s_mov_b32 s68, -2
	s_mov_b64 s[4:5], 0
	v_mov_b64_e32 v[4:5], 0
	v_mov_b64_e32 v[6:7], 0
	v_mov_b64_e32 v[8:9], 0
	v_mov_b64_e32 v[10:11], 0
	v_mov_b64_e32 v[12:13], 0
	v_mov_b64_e32 v[14:15], 0
	v_mov_b64_e32 v[16:17], 0
	v_mov_b64_e32 v[18:19], 0
	v_mov_b64_e32 v[20:21], 0
	v_mov_b64_e32 v[22:23], 0
	v_mov_b64_e32 v[24:25], 0
	v_mov_b64_e32 v[26:27], 0
	v_mov_b64_e32 v[28:29], 0
	v_mov_b64_e32 v[30:31], 0
	v_mov_b64_e32 v[32:33], 0
	v_mov_b64_e32 v[34:35], 0
	v_mov_b64_e32 v[36:37], 0
	v_mov_b64_e32 v[38:39], 0
	v_mov_b64_e32 v[40:41], 0
	v_mov_b64_e32 v[42:43], 0
	v_mov_b64_e32 v[44:45], 0
	v_mov_b64_e32 v[46:47], 0
	v_mov_b64_e32 v[48:49], 0
	v_mov_b64_e32 v[50:51], 0
	v_mov_b64_e32 v[52:53], 0
	v_mov_b64_e32 v[54:55], 0
	v_mov_b64_e32 v[56:57], 0
	v_mov_b64_e32 v[58:59], 0
	v_mov_b64_e32 v[60:61], 0
	v_mov_b64_e32 v[62:63], 0
	v_mov_b64_e32 v[64:65], 0
	v_mov_b64_e32 v[66:67], 0
	v_mov_b64_e32 v[68:69], 0
	v_mov_b64_e32 v[70:71], 0
	v_mov_b64_e32 v[72:73], 0
	v_mov_b64_e32 v[74:75], 0
	v_mov_b64_e32 v[76:77], 0
	v_mov_b64_e32 v[78:79], 0
	v_mov_b64_e32 v[80:81], 0
	v_mov_b64_e32 v[82:83], 0
	v_mov_b64_e32 v[84:85], 0
	v_mov_b64_e32 v[86:87], 0
	v_mov_b64_e32 v[88:89], 0
	v_mov_b64_e32 v[90:91], 0
	v_mov_b64_e32 v[92:93], 0
	v_mov_b64_e32 v[94:95], 0
	v_mov_b64_e32 v[96:97], 0
	v_mov_b64_e32 v[98:99], 0
	v_mov_b64_e32 v[100:101], 0
	v_mov_b64_e32 v[102:103], 0
	v_mov_b64_e32 v[104:105], 0
	v_mov_b64_e32 v[106:107], 0
	v_mov_b64_e32 v[108:109], 0
	v_mov_b64_e32 v[110:111], 0
	v_mov_b64_e32 v[112:113], 0
	v_mov_b64_e32 v[114:115], 0
	v_mov_b64_e32 v[116:117], 0
	v_mov_b64_e32 v[118:119], 0
	v_mov_b64_e32 v[120:121], 0
	v_mov_b64_e32 v[122:123], 0
	v_mov_b64_e32 v[124:125], 0
	v_mov_b64_e32 v[126:127], 0
	v_mov_b64_e32 v[128:129], 0
	v_lshl_add_u64 v[144:145], s[6:7], 0, v[138:139]
	v_lshl_add_u64 v[146:147], s[6:7], 0, v[140:141]
	s_add_u32 s6, s44, s4
	s_addc_u32 s7, s45, s5
	s_add_u32 s8, s6, 0x100
	s_addc_u32 s9, s7, 0
	s_add_u32 s69, s66, s4
	s_addc_u32 s78, s67, s5
	s_add_u32 s86, s6, 0x180
	s_addc_u32 s87, s7, 0
	s_cmpk_eq_i32 s4, 0xf00
	s_cselect_b32 s51, s30, s9
	s_cselect_b32 s50, s31, s8
	s_cselect_b32 s7, s39, s78
	s_cselect_b32 s6, s43, s69
	s_cselect_b32 s9, s65, s87
	s_cselect_b32 s8, s64, s86
	s_add_u32 s86, s44, s4
	s_addc_u32 s87, s45, s5
	s_add_u32 s86, s86, 0x80080
	s_addc_u32 s87, s87, 0
	v_add_u32_e32 v241, 0x10000, v150
	v_add_u32_e32 v242, 0x14000, v150
	v_add_u32_e32 v243, 0x18000, v150
	v_add_u32_e32 v244, 0x1c000, v150
	.p2align 6

; template <class Epi>
; DI void gemm_phase(LAS unsigned char* lds, const Gemm g, const StaticOrder& S, const Epi& E, const int tid) {
;     ...
;         const bool has_next = S.next(ui + 1, nxt);
;         const char* nA = has_next ? (const char*)g.A + (size_t)nxt.pm * tstepA : cA; const char* nB = has_next ? (const char*)g.Bt + (size_t)nxt.pn * tstepB : cB;
;         for (int t = 0; t < nt; t += 2) {
;             const bool last = (t == nt - 2);
;             const char* a1 = cA + PG8_KTA(t + 1);
;             const char* a2 = last ? nA : cA + PG8_KTA(t + 2); const char* b2 = last ? nB : cB + (size_t)(t + 2) * kstep;
;             const char* a3 = last ? nA + PG8_KTA(1) : cA + PG8_KTA(t + 3); const char* b3 = b2 + kstep;
;     ...
;         for (int a = 0; a < 2; ++a)
; #pragma unroll
;             for (int b = 0; b < 2; ++b)
; #pragma unroll
;                 for (int m = 0; m < 4; ++m)
; #pragma unroll
;                     for (int n = 0; n < 2; ++n) acc[a][b][m][n] = (f32x4){0.f, 0.f, 0.f, 0.f};
;         cur = nxt; cA = nA; cB = nB; ++ui;
.LBB0_285:
	s_ashr_i32 s41, s40, 31
	s_lshl_b64 s[6:7], s[40:41], 20
	s_add_u32 s44, s34, s6
	s_addc_u32 s45, s35, s7
	s_and_b64 s[6:7], s[38:39], exec
	s_cselect_b32 s30, s45, s5
	s_cselect_b32 s31, s44, s4
	s_add_u32 s38, s4, 0x100
	v_mov_b64_e32 v[2:3], 0
	s_addc_u32 s39, s5, 0
	s_movk_i32 s41, 0x3000
	s_mov_b32 s56, 0x18000
	s_mov_b32 s57, -2
	v_mov_b64_e32 v[4:5], 0
	v_mov_b64_e32 v[6:7], 0
	v_mov_b64_e32 v[8:9], 0
	v_mov_b64_e32 v[10:11], 0
	v_mov_b64_e32 v[12:13], 0
	v_mov_b64_e32 v[14:15], 0
	v_mov_b64_e32 v[16:17], 0
	v_mov_b64_e32 v[18:19], 0
	v_mov_b64_e32 v[20:21], 0
	v_mov_b64_e32 v[22:23], 0
	v_mov_b64_e32 v[24:25], 0
	v_mov_b64_e32 v[26:27], 0
	v_mov_b64_e32 v[28:29], 0
	v_mov_b64_e32 v[30:31], 0
	v_mov_b64_e32 v[32:33], 0
	v_mov_b64_e32 v[34:35], 0
	v_mov_b64_e32 v[36:37], 0
	v_mov_b64_e32 v[38:39], 0
	v_mov_b64_e32 v[40:41], 0
	v_mov_b64_e32 v[42:43], 0
	v_mov_b64_e32 v[44:45], 0
	v_mov_b64_e32 v[46:47], 0
	v_mov_b64_e32 v[48:49], 0
	v_mov_b64_e32 v[50:51], 0
	v_mov_b64_e32 v[52:53], 0
	v_mov_b64_e32 v[54:55], 0
	v_mov_b64_e32 v[56:57], 0
	v_mov_b64_e32 v[58:59], 0
	v_mov_b64_e32 v[60:61], 0
	v_mov_b64_e32 v[62:63], 0
	v_mov_b64_e32 v[64:65], 0
	v_mov_b64_e32 v[66:67], 0
	v_mov_b64_e32 v[68:69], 0
	v_mov_b64_e32 v[70:71], 0
	v_mov_b64_e32 v[72:73], 0
	v_mov_b64_e32 v[74:75], 0
	v_mov_b64_e32 v[76:77], 0
	v_mov_b64_e32 v[78:79], 0
	v_mov_b64_e32 v[80:81], 0
	v_mov_b64_e32 v[82:83], 0
	v_mov_b64_e32 v[84:85], 0
	v_mov_b64_e32 v[86:87], 0
	v_mov_b64_e32 v[88:89], 0
	v_mov_b64_e32 v[90:91], 0
	v_mov_b64_e32 v[92:93], 0
	v_mov_b64_e32 v[94:95], 0
	v_mov_b64_e32 v[96:97], 0
	v_mov_b64_e32 v[98:99], 0
	v_mov_b64_e32 v[100:101], 0
	v_mov_b64_e32 v[102:103], 0
	v_mov_b64_e32 v[104:105], 0
	v_mov_b64_e32 v[106:107], 0
	v_mov_b64_e32 v[108:109], 0
	v_mov_b64_e32 v[110:111], 0
	v_mov_b64_e32 v[112:113], 0
	v_mov_b64_e32 v[114:115], 0
	v_mov_b64_e32 v[116:117], 0
	v_mov_b64_e32 v[118:119], 0
	v_mov_b64_e32 v[120:121], 0
	v_mov_b64_e32 v[122:123], 0
	v_mov_b64_e32 v[124:125], 0
	v_mov_b64_e32 v[126:127], 0
	v_mov_b64_e32 v[128:129], 0
	v_add_u32_e32 v241, 0x10000, v139
	v_add_u32_e32 v242, 0x14000, v139
	v_add_u32_e32 v243, 0x18000, v139
	v_add_u32_e32 v244, 0x1c000, v139
	s_branch .LBB0_287
	.p2align 6
